# attention K/V prefetch loads in saddr form (16 fewer 64-bit VALU adds per two KV tiles per wave)
# speedup vs baseline: 1.0183x; 1.0015x over previous
.LBB0_708:
	s_mov_b64 s[2:3], s[0:1]
	s_mov_b32 s4, s12
	s_mov_b32 s5, s13
	s_load_dwordx2 s[4:5], s[2:3], 0x70
	s_load_dwordx2 s[34:35], s[2:3], 0xe8
	s_lshl_b64 s[2:3], s[50:51], 2
	v_mov_b32_e32 v145, v220
	s_waitcnt lgkmcnt(0)
	s_add_u32 s4, s4, s2
	s_addc_u32 s5, s5, s3
	s_add_u32 s2, s34, 0x200000
	s_addc_u32 s3, s35, 0
	s_bfe_u32 s6, s9, 0x10002
	s_lshl_b32 s10, s6, 12
	s_or_b32 s11, s10, 0x2000
	s_lshl_b32 s10, s9, 5
	s_lshl_b32 s6, s6, 20
	s_and_b32 s7, s9, 3
	s_and_b32 s22, s10, 0xf00
	s_add_i32 s6, s6, s8
	s_and_b32 s16, s9, 0xffffff80
	s_or_b32 s10, s11, s22
	s_lshl_b32 s6, s6, 1
	s_lshl_b32 s15, s7, 8
	s_add_u32 s6, s34, s6
	s_addc_u32 s18, s35, 0
	s_add_u32 s20, s6, s15
	s_addc_u32 s21, s18, 0
	s_add_u32 s48, s20, 0x600000
	s_addc_u32 s49, s21, 0
	s_add_u32 s56, s20, 0xa00000
	s_addc_u32 s57, s21, 0
	s_lshl_b32 s6, s11, 10
	s_add_u32 s6, s34, s6
	s_addc_u32 s11, s35, 0
	s_add_u32 s6, s6, s15
	s_addc_u32 s11, s11, 0
	s_add_u32 s36, s6, 0x68600000
	s_addc_u32 s43, s11, 0
	s_add_u32 s44, s6, 0x69600000
	s_addc_u32 s52, s11, 0
	s_mul_i32 s6, s10, 0x4800
	s_add_u32 s6, s34, s6
	s_addc_u32 s15, s35, 0
	s_add_u32 s11, s6, 0x2e600000
	s_addc_u32 s15, s15, 0
	s_lshl_b32 s6, s7, 9
	s_add_i32 s6, s6, s16
	v_ashrrev_i32_e32 v136, 4, v145
	s_ashr_i32 s7, s6, 31
	v_add_u32_e32 v138, 32, v136
	s_lshl_b64 s[6:7], s[6:7], 1
	v_lshlrev_b32_e32 v18, 3, v145
	v_ashrrev_i32_e32 v137, 31, v136
	v_ashrrev_i32_e32 v139, 31, v138
	s_add_u32 s18, s11, s6
	v_ashrrev_i32_e32 v228, 6, v145
	v_and_b32_e32 v144, 0x78, v18
	v_lshlrev_b64 v[132:133], 10, v[136:137]
	v_lshlrev_b64 v[134:135], 10, v[138:139]
	s_addc_u32 s19, s15, s7
	v_and_b32_e32 v227, 31, v145
	v_lshlrev_b32_e32 v188, 1, v144
	v_lshl_add_u64 v[0:1], s[56:57], 0, v[132:133]
	v_mov_b32_e32 v189, v177
	v_lshl_add_u64 v[2:3], s[56:57], 0, v[134:135]
	v_lshlrev_b32_e32 v229, 5, v228
	v_bfe_u32 v226, v145, 5, 1
	v_lshl_add_u64 v[0:1], v[0:1], 0, v[188:189]
	v_lshl_add_u64 v[2:3], v[2:3], 0, v[188:189]
	v_or_b32_e32 v19, v229, v227
	v_mov_b64_e32 v[16:17], s[18:19]
	global_load_dwordx4 v[8:11], v[0:1], off
	global_load_dwordx4 v[4:7], v[2:3], off
	v_lshl_add_u64 v[0:1], s[48:49], 0, v[132:133]
	v_lshl_add_u64 v[2:3], s[48:49], 0, v[134:135]
	v_mad_i64_i32 v[16:17], s[18:19], v19, s45, v[16:17]
	v_lshlrev_b32_e32 v190, 4, v226
	v_mov_b32_e32 v191, v177
	v_lshl_add_u64 v[0:1], v[0:1], 0, v[188:189]
	v_lshl_add_u64 v[2:3], v[2:3], 0, v[188:189]
	v_lshl_add_u64 v[16:17], v[16:17], 0, v[190:191]
	global_load_dwordx4 v[12:15], v[0:1], off
	s_nop 0
	global_load_dwordx4 v[0:3], v[2:3], off
	s_barrier
	global_load_dwordx4 v[162:165], v[16:17], off offset:160
	global_load_dwordx4 v[166:169], v[16:17], off offset:224
	v_and_b32_e32 v20, 32, v145
	global_load_dwordx4 v[154:157], v20, s[4:5] offset:464
	global_load_dwordx4 v[32:35], v20, s[4:5] offset:336
	global_load_dwordx4 v[178:181], v[16:17], off offset:128
	global_load_dwordx4 v[182:185], v[16:17], off offset:192
	global_load_dwordx4 v[44:47], v20, s[4:5] offset:320
	global_load_dwordx4 v[192:195], v20, s[4:5] offset:448
	global_load_dwordx4 v[120:123], v[16:17], off
	global_load_dwordx4 v[128:131], v[16:17], off offset:32
	global_load_dwordx4 v[200:203], v20, s[4:5] offset:400
	global_load_dwordx4 v[80:83], v20, s[4:5] offset:272
	global_load_dwordx4 v[210:213], v20, s[4:5] offset:384
	global_load_dwordx4 v[88:91], v20, s[4:5] offset:256
	global_load_dwordx4 v[116:119], v[16:17], off offset:64
	global_load_dwordx4 v[232:235], v[16:17], off offset:96
	global_load_dwordx4 v[108:111], v20, s[4:5]
	global_load_dwordx4 v[104:107], v20, s[4:5] offset:16
	global_load_dwordx4 v[100:103], v20, s[4:5] offset:64
	global_load_dwordx4 v[96:99], v20, s[4:5] offset:80
	global_load_dwordx4 v[112:115], v20, s[4:5] offset:128
	global_load_dwordx4 v[124:127], v20, s[4:5] offset:144
	global_load_dwordx4 v[236:239], v20, s[4:5] offset:192
	global_load_dwordx4 v[240:243], v20, s[4:5] offset:208
	v_and_b32_e32 v21, 0xfffff0, v136
	v_lshlrev_b32_e32 v22, 1, v136
	v_and_or_b32 v21, v22, 8, v21
	v_lshrrev_b32_e32 v22, 1, v136
	v_and_b32_e32 v23, 3, v136
	v_and_or_b32 v22, v22, 4, v23
	v_and_b32_e32 v23, 0xfffff0, v138
	v_lshlrev_b32_e32 v24, 1, v138
	v_and_or_b32 v23, v24, 8, v23
	v_lshrrev_b32_e32 v21, 1, v21
	v_bfe_u32 v18, v18, 5, 2
	v_lshrrev_b32_e32 v23, 1, v23
	v_or_b32_e32 v21, v21, v18
	v_or_b32_e32 v18, v23, v18
	v_lshlrev_b32_e32 v21, 9, v21
	v_lshlrev_b32_e32 v22, 6, v22
	v_lshlrev_b32_e32 v18, 9, v18
	v_and_b32_e32 v16, 48, v188
	v_or3_b32 v191, v18, v22, v16
	v_or3_b32 v231, v21, v22, v16
	v_or_b32_e32 v16, s22, v227
	v_add_u32_e32 v16, v16, v229
	v_ashrrev_i32_e32 v16, 1, v16
	v_and_b32_e32 v16, 0xffffffe0, v16
	v_ashrrev_i32_e32 v17, 31, v16
	v_lshl_add_u64 v[16:17], v[16:17], 3, s[2:3]
	v_lshlrev_b32_e32 v176, 6, v226
	v_lshl_add_u64 v[16:17], v[16:17], 0, v[176:177]
	global_load_dwordx4 v[68:71], v[16:17], off offset:48
	global_load_dwordx4 v[76:79], v[16:17], off offset:32
	global_load_dwordx4 v[84:87], v[16:17], off offset:16
	global_load_dwordx4 v[92:95], v[16:17], off
	global_load_dwordx4 v[48:51], v[16:17], off offset:176
	global_load_dwordx4 v[56:59], v[16:17], off offset:160
	global_load_dwordx4 v[64:67], v[16:17], off offset:144
	global_load_dwordx4 v[72:75], v[16:17], off offset:128
	v_lshlrev_b32_e32 v16, 8, v19
	v_and_b32_e32 v16, 0x3f00, v16
	v_mov_b32_e32 v17, v177
	v_lshl_add_u64 v[16:17], s[2:3], 0, v[16:17]
	v_lshl_add_u64 v[36:37], v[16:17], 0, v[176:177]
	global_load_dwordx4 v[28:31], v[36:37], off offset:48
	global_load_dwordx4 v[40:43], v[36:37], off offset:32
	global_load_dwordx4 v[52:55], v[36:37], off offset:16
	global_load_dwordx4 v[60:63], v[36:37], off
	global_load_dwordx4 v[16:19], v[36:37], off offset:176
	global_load_dwordx4 v[20:23], v[36:37], off offset:160
	global_load_dwordx4 v[24:27], v[36:37], off offset:144
	s_nop 0
	global_load_dwordx4 v[36:39], v[36:37], off offset:128
	v_lshlrev_b32_e32 v230, 4, v145
	s_add_i32 s2, 0, 0x10000
	s_cmp_lg_u32 0, -1
	s_cselect_b32 s4, 0, 0
	s_mov_b32 s16, s17
	s_mov_b32 s18, s17
	s_mov_b32 s19, s17
	s_mov_b32 s24, s17
	s_mov_b32 s25, s17
	s_mov_b32 s26, s17
	s_mov_b32 s27, s17
	s_mov_b32 s28, s17
	s_mov_b32 s29, s17
	s_mov_b32 s30, s17
	s_mov_b32 s31, s17
	s_mov_b32 s85, 4
	v_lshlrev_b32_e32 v176, 1, v144
	s_waitcnt vmcnt(31)
	v_lshlrev_b32_e32 v225, 16, v123
	v_mov_b32_e32 v146, v156
	v_mov_b32_e32 v152, v154
	v_lshlrev_b32_e32 v141, 16, v165
	v_lshlrev_b32_e32 v140, 16, v169
	v_and_b32_e32 v142, 0xffff0000, v169
	v_lshlrev_b32_e32 v154, 16, v167
	v_and_b32_e32 v156, 0xffff0000, v167
	v_lshlrev_b32_e32 v167, 16, v181
	v_and_b32_e32 v169, 0xffff0000, v181
	s_waitcnt vmcnt(21)
	v_mov_b32_e32 v181, v102
	s_waitcnt vmcnt(17)
	v_mov_b32_e32 v102, v239
	v_lshlrev_b32_e32 v239, 16, v120
	v_and_b32_e32 v143, 0xffff0000, v165
	v_mov_b32_e32 v165, v44
	v_mov_b32_e32 v44, v193
	v_lshlrev_b32_e32 v175, 16, v180
	v_and_b32_e32 v193, 0xffff0000, v180
	s_waitcnt vmcnt(16)
	v_mov_b32_e32 v218, v240
	v_mov_b32_e32 v219, v96
	v_mov_b32_e32 v96, v241
	v_mov_b32_e32 v180, v238
	v_and_b32_e32 v241, 0xffff0000, v120
	v_lshlrev_b32_e32 v238, 16, v116
	v_and_b32_e32 v240, 0xffff0000, v116
	v_mul_f32_e32 v116, v239, v239
	v_mov_b32_e32 v170, v202
	v_mov_b32_e32 v202, v212
	v_mov_b32_e32 v208, v210
	v_lshlrev_b32_e32 v210, 16, v235
	v_and_b32_e32 v212, 0xffff0000, v235
	v_mov_b32_e32 v235, v104
	v_mov_b32_e32 v104, v125
	v_lshlrev_b32_e32 v125, 16, v121
	v_fmac_f32_e32 v116, v241, v241
	v_and_b32_e32 v121, 0xffff0000, v121
	v_fmac_f32_e32 v116, v125, v125
	v_lshlrev_b32_e32 v205, 16, v178
	v_lshlrev_b32_e32 v204, 16, v182
	v_and_b32_e32 v207, 0xffff0000, v178
	v_and_b32_e32 v206, 0xffff0000, v182
	v_lshlrev_b32_e32 v178, 16, v233
	v_and_b32_e32 v182, 0xffff0000, v233
	v_mov_b32_e32 v233, v106
	v_mov_b32_e32 v106, v127
	v_lshlrev_b32_e32 v127, 16, v122
	v_fmac_f32_e32 v116, v121, v121
	v_mov_b32_e32 v187, v100
	v_mov_b32_e32 v100, v237
	v_and_b32_e32 v237, 0xffff0000, v122
	v_fmac_f32_e32 v116, v127, v127
	v_fmac_f32_e32 v116, v237, v237
	v_and_b32_e32 v123, 0xffff0000, v123
	v_fmac_f32_e32 v116, v225, v225
	v_mov_b32_e32 v147, v34
	v_mov_b32_e32 v34, v157
	v_lshlrev_b32_e32 v148, 16, v168
	v_mov_b32_e32 v153, v32
	v_and_b32_e32 v150, 0xffff0000, v168
	v_mov_b32_e32 v32, v155
	v_lshlrev_b32_e32 v155, 16, v163
	v_and_b32_e32 v157, 0xffff0000, v163
	v_lshlrev_b32_e32 v161, 16, v162
	v_lshlrev_b32_e32 v160, 16, v166
	v_and_b32_e32 v163, 0xffff0000, v162
	v_and_b32_e32 v162, 0xffff0000, v166
	v_lshlrev_b32_e32 v166, 16, v185
	v_and_b32_e32 v168, 0xffff0000, v185
	v_lshlrev_b32_e32 v185, 16, v128
	v_fmac_f32_e32 v116, v123, v123
	v_mov_b32_e32 v158, v194
	v_mov_b32_e32 v159, v46
	v_mov_b32_e32 v46, v195
	v_mov_b32_e32 v194, v200
	v_mov_b32_e32 v195, v80
	v_mov_b32_e32 v80, v201
	v_lshlrev_b32_e32 v197, 16, v179
	v_lshlrev_b32_e32 v196, 16, v183
	v_and_b32_e32 v201, 0xffff0000, v179
	v_and_b32_e32 v200, 0xffff0000, v183
	v_lshlrev_b32_e32 v179, 16, v129
	v_and_b32_e32 v183, 0xffff0000, v129
	v_and_b32_e32 v129, 0xffff0000, v128
	v_fmac_f32_e32 v116, v185, v185
	v_fmac_f32_e32 v116, v129, v129
	v_fmac_f32_e32 v116, v179, v179
	v_lshlrev_b32_e32 v217, 16, v130
	v_fmac_f32_e32 v116, v183, v183
	v_mov_b32_e32 v171, v82
	v_mov_b32_e32 v82, v203
	v_mov_b32_e32 v203, v90
	v_mov_b32_e32 v90, v213
	v_mov_b32_e32 v209, v88
	v_mov_b32_e32 v88, v211
	v_lshlrev_b32_e32 v211, 16, v131
	v_and_b32_e32 v213, 0xffff0000, v131
	v_and_b32_e32 v131, 0xffff0000, v130
	v_fmac_f32_e32 v116, v217, v217
	v_fmac_f32_e32 v116, v131, v131
	v_fmac_f32_e32 v116, v211, v211
	v_fmac_f32_e32 v116, v213, v213
	v_lshlrev_b32_e32 v216, 16, v234
	v_and_b32_e32 v130, 0xffff0000, v234
	v_mov_b32_e32 v234, v124
	v_lshlrev_b32_e32 v124, 16, v117
	v_and_b32_e32 v120, 0xffff0000, v117
	v_pk_fma_f32 v[116:117], v[238:239], v[238:239], v[116:117] op_sel_hi:[1,1,0]
	v_lshlrev_b32_e32 v149, 16, v164
	v_pk_fma_f32 v[116:117], v[240:241], v[240:241], v[116:117]
	v_and_b32_e32 v151, 0xffff0000, v164
	v_pk_fma_f32 v[116:117], v[124:125], v[124:125], v[116:117]
	v_mov_b32_e32 v164, v192
	v_lshlrev_b32_e32 v174, 16, v184
	v_and_b32_e32 v192, 0xffff0000, v184
	v_lshlrev_b32_e32 v184, 16, v232
	v_and_b32_e32 v128, 0xffff0000, v232
	v_mov_b32_e32 v232, v126
	v_lshlrev_b32_e32 v126, 16, v118
	v_pk_fma_f32 v[116:117], v[120:121], v[120:121], v[116:117]
	v_mov_b32_e32 v186, v236
	v_and_b32_e32 v236, 0xffff0000, v118
	v_pk_fma_f32 v[116:117], v[126:127], v[126:127], v[116:117]
	v_lshlrev_b32_e32 v224, 16, v119
	v_pk_fma_f32 v[116:117], v[236:237], v[236:237], v[116:117]
	v_and_b32_e32 v122, 0xffff0000, v119
	v_pk_fma_f32 v[116:117], v[224:225], v[224:225], v[116:117]
	v_mul_f32_e32 v118, v205, v205
	v_pk_fma_f32 v[116:117], v[122:123], v[122:123], v[116:117]
	v_mov_b32_e32 v214, v242
	v_pk_fma_f32 v[116:117], v[184:185], v[184:185], v[116:117]
	v_mov_b32_e32 v215, v98
	v_pk_fma_f32 v[116:117], v[128:129], v[128:129], v[116:117]
	v_mov_b32_e32 v98, v243
	v_pk_fma_f32 v[116:117], v[178:179], v[178:179], v[116:117]
	v_mov_b32_e32 v242, v156
	v_pk_fma_f32 v[116:117], v[182:183], v[182:183], v[116:117]
	v_mov_b32_e32 v243, v154
	v_pk_fma_f32 v[116:117], v[216:217], v[216:217], v[116:117]
	v_mov_b32_e32 v198, v150
	v_pk_fma_f32 v[116:117], v[130:131], v[130:131], v[116:117]
	v_mov_b32_e32 v199, v148
	v_pk_fma_f32 v[116:117], v[210:211], v[210:211], v[116:117]
	v_mov_b32_e32 v172, v142
	v_pk_fma_f32 v[116:117], v[212:213], v[212:213], v[116:117]
	v_mov_b32_e32 v173, v140
	v_pk_add_f32 v[116:117], v[118:119], v[116:117] op_sel_hi:[0,1]
	v_mul_f32_e32 v118, v207, v207
	v_pk_add_f32 v[116:117], v[118:119], v[116:117] op_sel_hi:[0,1]
	v_mul_f32_e32 v118, v197, v197
	v_pk_add_f32 v[116:117], v[118:119], v[116:117] op_sel_hi:[0,1]
	v_mul_f32_e32 v118, v201, v201
	v_pk_add_f32 v[116:117], v[118:119], v[116:117] op_sel_hi:[0,1]
	v_mul_f32_e32 v118, v175, v175
	v_pk_add_f32 v[116:117], v[118:119], v[116:117] op_sel_hi:[0,1]
	v_mul_f32_e32 v118, v193, v193
	v_pk_add_f32 v[116:117], v[118:119], v[116:117] op_sel_hi:[0,1]
	v_mul_f32_e32 v118, v167, v167
	v_pk_add_f32 v[116:117], v[118:119], v[116:117] op_sel_hi:[0,1]
	v_mul_f32_e32 v118, v169, v169
	v_pk_add_f32 v[116:117], v[118:119], v[116:117] op_sel_hi:[0,1]
	v_mul_f32_e32 v118, v161, v161
	v_pk_add_f32 v[116:117], v[118:119], v[116:117] op_sel_hi:[0,1]
	v_mul_f32_e32 v118, v163, v163
	v_pk_add_f32 v[116:117], v[118:119], v[116:117] op_sel_hi:[0,1]
	v_mul_f32_e32 v118, v155, v155
	v_pk_add_f32 v[116:117], v[118:119], v[116:117] op_sel_hi:[0,1]
	v_mul_f32_e32 v118, v157, v157
	v_pk_add_f32 v[116:117], v[118:119], v[116:117] op_sel_hi:[0,1]
	v_mul_f32_e32 v118, v149, v149
	v_pk_add_f32 v[116:117], v[118:119], v[116:117] op_sel_hi:[0,1]
	v_mul_f32_e32 v118, v151, v151
	v_pk_add_f32 v[116:117], v[118:119], v[116:117] op_sel_hi:[0,1]
	v_mul_f32_e32 v118, v141, v141
	v_pk_add_f32 v[116:117], v[118:119], v[116:117] op_sel_hi:[0,1]
	v_mul_f32_e32 v118, v143, v143
	v_pk_add_f32 v[116:117], v[118:119], v[116:117] op_sel_hi:[0,1]
	v_pk_fma_f32 v[116:117], v[204:205], v[204:205], v[116:117]
	v_mul_f32_e32 v118, v154, v154
	v_pk_fma_f32 v[116:117], v[206:207], v[206:207], v[116:117]
	s_nop 0
	v_pk_fma_f32 v[116:117], v[196:197], v[196:197], v[116:117]
	s_nop 0
	v_pk_fma_f32 v[116:117], v[200:201], v[200:201], v[116:117]
	s_nop 0
	v_pk_fma_f32 v[116:117], v[174:175], v[174:175], v[116:117]
	s_nop 0
	v_pk_fma_f32 v[116:117], v[192:193], v[192:193], v[116:117]
	s_nop 0
	v_pk_fma_f32 v[116:117], v[166:167], v[166:167], v[116:117]
	s_nop 0
	v_pk_fma_f32 v[116:117], v[168:169], v[168:169], v[116:117]
	s_nop 0
	v_pk_fma_f32 v[116:117], v[160:161], v[160:161], v[116:117]
	s_nop 0
	v_pk_fma_f32 v[116:117], v[162:163], v[162:163], v[116:117]
	s_nop 0
	v_pk_add_f32 v[116:117], v[118:119], v[116:117] op_sel_hi:[0,1]
	v_mov_b32_e32 v119, v110
	v_pk_fma_f32 v[116:117], v[242:243], v[242:243], v[116:117]
	v_mul_f32_e32 v110, v148, v148
	v_pk_add_f32 v[116:117], v[110:111], v[116:117] op_sel_hi:[0,1]
	v_pk_fma_f32 v[116:117], v[198:199], v[198:199], v[116:117]
	v_mul_f32_e32 v110, v140, v140
	v_pk_add_f32 v[116:117], v[110:111], v[116:117] op_sel_hi:[0,1]
	v_pk_fma_f32 v[116:117], v[172:173], v[172:173], v[116:117]
	v_mov_b32_e32 v118, v114
	v_mov_b32_e32 v110, v116
	s_nop 1
	v_permlane32_swap_b32_e32 v116, v110
	v_add_f32_e32 v110, v116, v110
	v_fmamk_f32 v110, v110, 0x3c000000, v221
	v_mul_f32_e32 v114, 0x4b800000, v110
	v_cmp_gt_f32_e32 vcc, s42, v110
	s_nop 1
	v_cndmask_b32_e32 v110, v110, v114, vcc
	v_rsq_f32_e32 v116, v110
	v_mov_b32_e32 v110, v115
	v_mov_b32_e32 v115, v108
	v_mov_b32_e32 v114, v112
	v_mul_f32_e32 v108, 0x45800000, v116
	v_cndmask_b32_e32 v112, v116, v108, vcc
	v_pk_mul_f32 v[114:115], v[114:115], v[112:113] op_sel_hi:[1,0]
	v_mov_b32_e32 v108, v113
	v_pk_mul_f32 v[114:115], v[114:115], v[238:239]
	v_pk_mul_f32 v[116:117], v[234:235], v[112:113] op_sel_hi:[1,0]
	v_pk_mul_f32 v[108:109], v[108:109], v[112:113] op_sel_hi:[1,0]
	v_pk_mul_f32 v[118:119], v[118:119], v[112:113] op_sel_hi:[1,0]
	v_pk_mul_f32 v[110:111], v[110:111], v[112:113] op_sel_hi:[1,0]
	v_pk_mul_f32 v[106:107], v[106:107], v[112:113] op_sel_hi:[1,0]
	v_pk_mul_f32 v[100:101], v[100:101], v[112:113] op_sel_hi:[1,0]
	v_pk_mul_f32 v[96:97], v[96:97], v[112:113] op_sel_hi:[1,0]
	v_pk_mul_f32 v[172:173], v[112:113], v[194:195] op_sel_hi:[0,1]
	v_pk_mul_f32 v[32:33], v[112:113], v[32:33] op_sel_hi:[0,1]
	v_pk_mul_f32 v[116:117], v[116:117], v[126:127]
	v_pk_mul_f32 v[108:109], v[108:109], v[240:241]
	v_pk_mul_f32 v[104:105], v[104:105], v[112:113] op_sel_hi:[1,0]
	v_pk_mul_f32 v[118:119], v[118:119], v[124:125]
	v_pk_mul_f32 v[124:125], v[232:233], v[112:113] op_sel_hi:[1,0]
	v_pk_mul_f32 v[110:111], v[110:111], v[120:121]
	v_pk_mul_f32 v[106:107], v[106:107], v[122:123]
	v_pk_mul_f32 v[120:121], v[186:187], v[112:113] op_sel_hi:[1,0]
	v_pk_mul_f32 v[122:123], v[218:219], v[112:113] op_sel_hi:[1,0]
	v_pk_mul_f32 v[100:101], v[100:101], v[128:129]
	v_pk_mul_f32 v[96:97], v[96:97], v[130:131]
	v_pk_mul_f32 v[126:127], v[180:181], v[112:113] op_sel_hi:[1,0]
	v_pk_mul_f32 v[128:129], v[214:215], v[112:113] op_sel_hi:[1,0]
	v_pk_mul_f32 v[102:103], v[102:103], v[112:113] op_sel_hi:[1,0]
	v_pk_mul_f32 v[98:99], v[98:99], v[112:113] op_sel_hi:[1,0]
	v_pk_mul_f32 v[130:131], v[112:113], v[208:209] op_sel_hi:[0,1]
	v_pk_mul_f32 v[172:173], v[172:173], v[174:175]
	v_pk_mul_f32 v[88:89], v[112:113], v[88:89] op_sel_hi:[0,1]
	v_pk_mul_f32 v[80:81], v[112:113], v[80:81] op_sel_hi:[0,1]
	v_pk_mul_f32 v[174:175], v[112:113], v[202:203] op_sel_hi:[0,1]
	v_pk_mul_f32 v[170:171], v[112:113], v[170:171] op_sel_hi:[0,1]
	v_pk_mul_f32 v[90:91], v[112:113], v[90:91] op_sel_hi:[0,1]
	v_pk_mul_f32 v[82:83], v[112:113], v[82:83] op_sel_hi:[0,1]
	v_pk_mul_f32 v[164:165], v[112:113], v[164:165] op_sel_hi:[0,1]
	v_pk_mul_f32 v[152:153], v[112:113], v[152:153] op_sel_hi:[0,1]
	v_pk_mul_f32 v[44:45], v[112:113], v[44:45] op_sel_hi:[0,1]
	v_pk_mul_f32 v[32:33], v[32:33], v[150:151]
	v_pk_mul_f32 v[150:151], v[112:113], v[158:159] op_sel_hi:[0,1]
	v_pk_mul_f32 v[146:147], v[112:113], v[146:147] op_sel_hi:[0,1]
	v_pk_mul_f32 v[46:47], v[112:113], v[46:47] op_sel_hi:[0,1]
	v_pk_mul_f32 v[34:35], v[112:113], v[34:35] op_sel_hi:[0,1]
	s_waitcnt vmcnt(12)
	v_pk_mul_f32 v[112:113], v[114:115], v[92:93] op_sel:[1,0] op_sel_hi:[0,1]
	v_pk_mul_f32 v[92:93], v[114:115], v[92:93]
	v_sub_f32_e32 v112, v112, v113
	v_add_f32_e32 v113, v93, v92
	v_pk_mul_f32 v[92:93], v[108:109], v[94:95] op_sel:[1,0] op_sel_hi:[0,1]
	v_sub_f32_e32 v114, v92, v93
	v_pk_mul_f32 v[92:93], v[108:109], v[94:95]
	v_pk_mul_f32 v[104:105], v[104:105], v[236:237]
	v_add_f32_e32 v94, v93, v92
	v_pk_mul_f32 v[92:93], v[118:119], v[84:85] op_sel:[1,0] op_sel_hi:[0,1]
	v_pk_mul_f32 v[84:85], v[118:119], v[84:85]
	v_sub_f32_e32 v92, v92, v93
	v_add_f32_e32 v93, v85, v84
	v_pk_mul_f32 v[84:85], v[110:111], v[86:87] op_sel:[1,0] op_sel_hi:[0,1]
	v_sub_f32_e32 v95, v84, v85
	v_pk_mul_f32 v[84:85], v[110:111], v[86:87]
	v_pk_mul_f32 v[124:125], v[124:125], v[224:225]
	v_add_f32_e32 v86, v85, v84
	v_pk_mul_f32 v[84:85], v[116:117], v[76:77] op_sel:[1,0] op_sel_hi:[0,1]
	v_pk_mul_f32 v[76:77], v[116:117], v[76:77]
	v_sub_f32_e32 v84, v84, v85
	v_add_f32_e32 v85, v77, v76
	v_pk_mul_f32 v[76:77], v[104:105], v[78:79] op_sel:[1,0] op_sel_hi:[0,1]
	v_sub_f32_e32 v87, v76, v77
	v_pk_mul_f32 v[76:77], v[104:105], v[78:79]
	v_pk_mul_f32 v[120:121], v[120:121], v[184:185]
	v_add_f32_e32 v78, v77, v76
	v_pk_mul_f32 v[76:77], v[124:125], v[68:69] op_sel:[1,0] op_sel_hi:[0,1]
	v_pk_mul_f32 v[68:69], v[124:125], v[68:69]
	v_sub_f32_e32 v76, v76, v77
	v_add_f32_e32 v77, v69, v68
	v_pk_mul_f32 v[68:69], v[106:107], v[70:71] op_sel:[1,0] op_sel_hi:[0,1]
	v_sub_f32_e32 v79, v68, v69
	v_pk_mul_f32 v[68:69], v[106:107], v[70:71]
	v_pk_mul_f32 v[126:127], v[126:127], v[178:179]
	v_add_f32_e32 v70, v69, v68
	s_waitcnt vmcnt(8)
	v_pk_mul_f32 v[68:69], v[120:121], v[72:73] op_sel:[1,0] op_sel_hi:[0,1]
	v_sub_f32_e32 v71, v68, v69
	v_pk_mul_f32 v[68:69], v[120:121], v[72:73]
	v_pk_mul_f32 v[102:103], v[102:103], v[182:183]
	v_add_f32_e32 v72, v69, v68
	v_pk_mul_f32 v[68:69], v[100:101], v[74:75] op_sel:[1,0] op_sel_hi:[0,1]
	v_sub_f32_e32 v73, v68, v69
	v_pk_mul_f32 v[68:69], v[100:101], v[74:75]
	v_pk_mul_f32 v[122:123], v[122:123], v[216:217]
	v_add_f32_e32 v74, v69, v68
	v_pk_mul_f32 v[68:69], v[126:127], v[64:65] op_sel:[1,0] op_sel_hi:[0,1]
	v_pk_mul_f32 v[64:65], v[126:127], v[64:65]
	v_sub_f32_e32 v68, v68, v69
	v_add_f32_e32 v69, v65, v64
	v_pk_mul_f32 v[64:65], v[102:103], v[66:67] op_sel:[1,0] op_sel_hi:[0,1]
	v_sub_f32_e32 v75, v64, v65
	v_pk_mul_f32 v[64:65], v[102:103], v[66:67]
	v_pk_mul_f32 v[128:129], v[128:129], v[210:211]
	v_add_f32_e32 v66, v65, v64
	v_pk_mul_f32 v[64:65], v[122:123], v[56:57] op_sel:[1,0] op_sel_hi:[0,1]
	v_pk_mul_f32 v[56:57], v[122:123], v[56:57]
	v_sub_f32_e32 v64, v64, v65
	v_add_f32_e32 v65, v57, v56
	v_pk_mul_f32 v[56:57], v[96:97], v[58:59] op_sel:[1,0] op_sel_hi:[0,1]
	v_sub_f32_e32 v67, v56, v57
	v_pk_mul_f32 v[56:57], v[96:97], v[58:59]
	v_pk_mul_f32 v[98:99], v[98:99], v[212:213]
	v_add_f32_e32 v58, v57, v56
	v_pk_mul_f32 v[56:57], v[128:129], v[48:49] op_sel:[1,0] op_sel_hi:[0,1]
	v_pk_mul_f32 v[48:49], v[128:129], v[48:49]
	v_sub_f32_e32 v56, v56, v57
	v_add_f32_e32 v57, v49, v48
	v_pk_mul_f32 v[48:49], v[98:99], v[50:51] op_sel:[1,0] op_sel_hi:[0,1]
	v_pk_mul_f32 v[130:131], v[130:131], v[204:205]
	v_sub_f32_e32 v59, v48, v49
	v_pk_mul_f32 v[48:49], v[98:99], v[50:51]
	v_pk_mul_f32 v[88:89], v[88:89], v[206:207]
	v_add_f32_e32 v50, v49, v48
	s_waitcnt vmcnt(4)
	v_pk_mul_f32 v[48:49], v[130:131], v[60:61] op_sel:[1,0] op_sel_hi:[0,1]
	v_sub_f32_e32 v51, v48, v49
	v_pk_mul_f32 v[48:49], v[130:131], v[60:61]
	v_pk_mul_f32 v[174:175], v[174:175], v[196:197]
	v_add_f32_e32 v60, v49, v48
	v_pk_mul_f32 v[48:49], v[88:89], v[62:63] op_sel:[1,0] op_sel_hi:[0,1]
	v_sub_f32_e32 v61, v48, v49
	v_pk_mul_f32 v[48:49], v[88:89], v[62:63]
	v_pk_mul_f32 v[90:91], v[90:91], v[200:201]
	v_add_f32_e32 v62, v49, v48
	v_pk_mul_f32 v[48:49], v[174:175], v[52:53] op_sel:[1,0] op_sel_hi:[0,1]
	v_sub_f32_e32 v63, v48, v49
	v_pk_mul_f32 v[48:49], v[174:175], v[52:53]
	v_pk_mul_f32 v[80:81], v[80:81], v[192:193]
	v_add_f32_e32 v52, v49, v48
	v_pk_mul_f32 v[48:49], v[90:91], v[54:55] op_sel:[1,0] op_sel_hi:[0,1]
	v_sub_f32_e32 v53, v48, v49
	v_pk_mul_f32 v[48:49], v[90:91], v[54:55]
	v_pk_mul_f32 v[166:167], v[170:171], v[166:167]
	v_add_f32_e32 v54, v49, v48
	v_pk_mul_f32 v[48:49], v[172:173], v[40:41] op_sel:[1,0] op_sel_hi:[0,1]
	v_pk_mul_f32 v[40:41], v[172:173], v[40:41]
	v_sub_f32_e32 v48, v48, v49
	v_add_f32_e32 v49, v41, v40
	v_pk_mul_f32 v[40:41], v[80:81], v[42:43] op_sel:[1,0] op_sel_hi:[0,1]
	v_sub_f32_e32 v55, v40, v41
	v_pk_mul_f32 v[40:41], v[80:81], v[42:43]
	v_pk_mul_f32 v[82:83], v[82:83], v[168:169]
	v_add_f32_e32 v42, v41, v40
	v_pk_mul_f32 v[40:41], v[166:167], v[28:29] op_sel:[1,0] op_sel_hi:[0,1]
	v_pk_mul_f32 v[28:29], v[166:167], v[28:29]
	v_sub_f32_e32 v40, v40, v41
	v_add_f32_e32 v41, v29, v28
	v_pk_mul_f32 v[28:29], v[82:83], v[30:31] op_sel:[1,0] op_sel_hi:[0,1]
	v_pk_mul_f32 v[160:161], v[164:165], v[160:161]
	v_sub_f32_e32 v43, v28, v29
	v_pk_mul_f32 v[28:29], v[82:83], v[30:31]
	v_pk_mul_f32 v[44:45], v[44:45], v[162:163]
	v_add_f32_e32 v30, v29, v28
	s_waitcnt vmcnt(0)
	v_pk_mul_f32 v[28:29], v[160:161], v[36:37] op_sel:[1,0] op_sel_hi:[0,1]
	v_sub_f32_e32 v31, v28, v29
	v_pk_mul_f32 v[28:29], v[160:161], v[36:37]
	v_pk_mul_f32 v[150:151], v[150:151], v[154:155]
	v_add_f32_e32 v36, v29, v28
	v_pk_mul_f32 v[28:29], v[44:45], v[38:39] op_sel:[1,0] op_sel_hi:[0,1]
	v_sub_f32_e32 v37, v28, v29
	v_pk_mul_f32 v[28:29], v[44:45], v[38:39]
	v_pk_mul_f32 v[46:47], v[46:47], v[156:157]
	v_add_f32_e32 v38, v29, v28
	v_pk_mul_f32 v[28:29], v[150:151], v[24:25] op_sel:[1,0] op_sel_hi:[0,1]
	v_pk_mul_f32 v[24:25], v[150:151], v[24:25]
	v_sub_f32_e32 v28, v28, v29
	v_add_f32_e32 v29, v25, v24
	v_pk_mul_f32 v[24:25], v[46:47], v[26:27] op_sel:[1,0] op_sel_hi:[0,1]
	v_pk_mul_f32 v[148:149], v[152:153], v[148:149]
	v_sub_f32_e32 v39, v24, v25
	v_pk_mul_f32 v[24:25], v[46:47], v[26:27]
	v_pk_mul_f32 v[140:141], v[146:147], v[140:141]
	v_add_f32_e32 v26, v25, v24
	v_pk_mul_f32 v[24:25], v[148:149], v[20:21] op_sel:[1,0] op_sel_hi:[0,1]
	v_pk_mul_f32 v[20:21], v[148:149], v[20:21]
	v_sub_f32_e32 v24, v24, v25
	v_add_f32_e32 v25, v21, v20
	v_pk_mul_f32 v[20:21], v[32:33], v[22:23] op_sel:[1,0] op_sel_hi:[0,1]
	v_sub_f32_e32 v27, v20, v21
	v_pk_mul_f32 v[20:21], v[32:33], v[22:23]
	v_pk_mul_f32 v[34:35], v[34:35], v[142:143]
	v_add_f32_e32 v22, v21, v20
	v_pk_mul_f32 v[20:21], v[140:141], v[16:17] op_sel:[1,0] op_sel_hi:[0,1]
	v_pk_mul_f32 v[16:17], v[140:141], v[16:17]
	v_sub_f32_e32 v20, v20, v21
	v_add_f32_e32 v21, v17, v16
	v_pk_mul_f32 v[16:17], v[34:35], v[18:19] op_sel:[1,0] op_sel_hi:[0,1]
	v_sub_f32_e32 v23, v16, v17
	v_pk_mul_f32 v[16:17], v[34:35], v[18:19]
	v_add_u32_e32 v200, 0, v231
	v_add_u32_e32 v201, 0, v191
	v_add_f32_e32 v16, v17, v16
	v_cvt_pk_bf16_f32 v124, v112, v114
	v_cvt_pk_bf16_f32 v125, v92, v95
	v_cvt_pk_bf16_f32 v126, v84, v87
	v_cvt_pk_bf16_f32 v127, v76, v79
	v_cvt_pk_bf16_f32 v120, v71, v73
	v_cvt_pk_bf16_f32 v121, v68, v75
	v_cvt_pk_bf16_f32 v122, v64, v67
	v_cvt_pk_bf16_f32 v123, v56, v59
	v_cvt_pk_bf16_f32 v116, v113, v94
	v_cvt_pk_bf16_f32 v117, v93, v86
	v_cvt_pk_bf16_f32 v118, v85, v78
	v_cvt_pk_bf16_f32 v119, v77, v70
	v_cvt_pk_bf16_f32 v112, v72, v74
	v_cvt_pk_bf16_f32 v113, v69, v66
	v_cvt_pk_bf16_f32 v114, v65, v58
	v_cvt_pk_bf16_f32 v115, v57, v50
	v_cvt_pk_bf16_f32 v108, v51, v61
	v_cvt_pk_bf16_f32 v109, v63, v53
	v_cvt_pk_bf16_f32 v110, v48, v55
	v_cvt_pk_bf16_f32 v111, v40, v43
	v_cvt_pk_bf16_f32 v104, v31, v37
	v_cvt_pk_bf16_f32 v105, v28, v39
	v_cvt_pk_bf16_f32 v106, v24, v27
	v_cvt_pk_bf16_f32 v107, v20, v23
	v_cvt_pk_bf16_f32 v100, v60, v62
	v_cvt_pk_bf16_f32 v101, v52, v54
	v_cvt_pk_bf16_f32 v102, v49, v42
	v_cvt_pk_bf16_f32 v103, v41, v30
	v_cvt_pk_bf16_f32 v96, v36, v38
	v_cvt_pk_bf16_f32 v97, v29, v26
	v_cvt_pk_bf16_f32 v98, v25, v22
	v_cvt_pk_bf16_f32 v99, v21, v16
	s_waitcnt vmcnt(0)
	ds_write_b128 v200, v[8:11]
	ds_write_b128 v201, v[4:7]
	v_lshlrev_b32_e32 v4, 8, v136
	v_and_b32_e32 v5, 0x70, v145
	v_bitop3_b32 v4, v188, v4, v5 bitop3:0xde
	v_add_u32_e32 v202, 0, v4
	v_lshlrev_b32_e32 v4, 8, v138
	v_bitop3_b32 v4, v188, v4, v5 bitop3:0xde
	v_add_u32_e32 v203, 0, v4
	v_lshlrev_b32_e32 v8, 8, v227
	v_and_b32_e32 v9, 0x70, v230
	ds_write_b128 v202, v[12:15] offset:32768
	ds_write_b128 v203, v[0:3] offset:32768
	v_bitop3_b32 v0, v190, v8, v9 bitop3:0xde
	v_add_u32_e32 v204, 0, v0
	s_waitcnt lgkmcnt(0)
	s_barrier
	ds_read_b128 v[0:3], v204 offset:32768
	ds_read_b128 v[4:7], v204 offset:40960
	s_waitcnt lgkmcnt(1)
	v_mfma_f32_32x32x16_bf16 v[32:47], v[0:3], v[124:127], 0
	v_or_b32_e32 v0, 32, v190
	v_bitop3_b32 v0, v0, v8, v9 bitop3:0xde
	v_add_u32_e32 v207, 0, v0
	v_and_b32_e32 v196, 63, v145
	v_lshlrev_b32_e32 v10, 3, v196
	v_and_b32_e32 v11, 0xc0, v230
	v_lshlrev_b64 v[64:65], 9, v[136:137]
	s_waitcnt lgkmcnt(0)
	v_mfma_f32_32x32x16_bf16 v[16:31], v[4:7], v[124:127], 0
	ds_read_b128 v[0:3], v207 offset:32768
	ds_read_b128 v[4:7], v207 offset:40960
	v_lshlrev_b64 v[66:67], 9, v[138:139]
	v_mov_b32_e32 v197, 0
	v_lshlrev_b64 v[192:193], 1, v[64:65]
	v_lshlrev_b64 v[194:195], 1, v[66:67]
	s_waitcnt lgkmcnt(1)
	v_mfma_f32_32x32x16_bf16 v[32:47], v[0:3], v[120:123], v[32:47]
	v_or_b32_e32 v0, 64, v190
	v_bitop3_b32 v0, v0, v8, v9 bitop3:0xde
	v_add_u32_e32 v209, 0, v0
	s_waitcnt lgkmcnt(0)
	v_mfma_f32_32x32x16_bf16 v[16:31], v[4:7], v[120:123], v[16:31]
	ds_read_b128 v[0:3], v209 offset:32768
	ds_read_b128 v[4:7], v209 offset:40960
	s_waitcnt lgkmcnt(1)
	v_mfma_f32_32x32x16_bf16 v[32:47], v[0:3], v[116:119], v[32:47]
	v_or_b32_e32 v0, 0x60, v190
	v_bitop3_b32 v0, v0, v8, v9 bitop3:0xde
	v_add_u32_e32 v205, 0, v0
	s_waitcnt lgkmcnt(0)
	v_mfma_f32_32x32x16_bf16 v[16:31], v[4:7], v[116:119], v[16:31]
	ds_read_b128 v[0:3], v205 offset:32768
	ds_read_b128 v[4:7], v205 offset:40960
	s_waitcnt lgkmcnt(1)
	v_mfma_f32_32x32x16_bf16 v[32:47], v[0:3], v[112:115], v[32:47]
	v_or_b32_e32 v0, 0x80, v190
	v_bitop3_b32 v0, v0, v8, v9 bitop3:0xde
	v_add_u32_e32 v206, 0, v0
	s_waitcnt lgkmcnt(0)
	v_mfma_f32_32x32x16_bf16 v[16:31], v[4:7], v[112:115], v[16:31]
	ds_read_b128 v[0:3], v206 offset:32768
	ds_read_b128 v[4:7], v206 offset:40960
	s_waitcnt lgkmcnt(1)
	v_mfma_f32_32x32x16_bf16 v[32:47], v[0:3], v[108:111], v[32:47]
	v_or_b32_e32 v0, 0xa0, v190
	v_bitop3_b32 v0, v0, v8, v9 bitop3:0xde
	v_add_u32_e32 v208, 0, v0
	s_waitcnt lgkmcnt(0)
	v_mfma_f32_32x32x16_bf16 v[16:31], v[4:7], v[108:111], v[16:31]
	ds_read_b128 v[0:3], v208 offset:32768
	ds_read_b128 v[4:7], v208 offset:40960
	s_waitcnt lgkmcnt(1)
	v_mfma_f32_32x32x16_bf16 v[32:47], v[0:3], v[104:107], v[32:47]
	v_or_b32_e32 v0, 0xc0, v190
	v_bitop3_b32 v0, v0, v8, v9 bitop3:0xde
	v_add_u32_e32 v210, 0, v0
	ds_read_b128 v[0:3], v210 offset:32768
	s_waitcnt lgkmcnt(1)
	v_mfma_f32_32x32x16_bf16 v[16:31], v[4:7], v[104:107], v[16:31]
	v_and_b32_e32 v4, 0x3fffffc0, v145
	v_lshl_add_u32 v191, v4, 2, s2
	ds_read_b128 v[4:7], v210 offset:40960
	s_waitcnt lgkmcnt(1)
	v_mfma_f32_32x32x16_bf16 v[32:47], v[0:3], v[100:103], v[32:47]
	v_or_b32_e32 v0, 0xe0, v190
	v_bitop3_b32 v0, v0, v8, v9 bitop3:0xde
	v_add_u32_e32 v211, 0, v0
	ds_read_b128 v[0:3], v211 offset:32768
	s_waitcnt lgkmcnt(1)
	v_mfma_f32_32x32x16_bf16 v[16:31], v[4:7], v[100:103], v[16:31]
	v_lshlrev_b32_e32 v5, 1, v145
	v_and_or_b32 v4, v10, 24, v11
	v_and_b32_e32 v5, 32, v5
	v_and_b32_e32 v6, 0x100, v10
	v_or3_b32 v69, v4, v5, v6
	ds_read_b128 v[4:7], v211 offset:40960
	v_add_u32_e32 v199, s4, v69
	s_waitcnt lgkmcnt(1)
	v_mfma_f32_32x32x16_bf16 v[32:47], v[0:3], v[96:99], v[32:47]
	s_waitcnt lgkmcnt(0)
	v_mfma_f32_32x32x16_bf16 v[16:31], v[4:7], v[96:99], v[16:31]
	s_nop 9
	v_max_f32_e32 v0, v33, v33
	v_max_f32_e32 v1, v32, v32
	v_max_f32_e32 v0, v1, v0
	v_max3_f32 v0, v0, v34, v35
	v_max3_f32 v0, v0, v36, v37
	v_max3_f32 v0, v0, v38, v39
	v_max3_f32 v0, v0, v40, v41
	v_max3_f32 v0, v0, v42, v43
	v_max3_f32 v0, v0, v44, v45
	v_max3_f32 v0, v0, v46, v47
	v_max3_f32 v0, v0, v16, v17
	v_max3_f32 v0, v0, v18, v19
	v_max3_f32 v0, v0, v20, v21
	v_max3_f32 v0, v0, v22, v23
	v_max3_f32 v0, v0, v24, v25
	v_max3_f32 v0, v0, v26, v27
	v_max3_f32 v0, v0, v28, v29
	v_max3_f32 v0, v0, v30, v31
	v_mov_b32_e32 v1, v0
	s_nop 1
	v_permlane32_swap_b32_e32 v0, v1
	v_max_f32_e32 v1, v1, v1
	v_max_f32_e32 v0, v0, v0
	v_max_f32_e32 v0, v0, v1
	v_add_f32_e32 v1, 0x7149f2ca, v0
	v_cmp_ge_f32_e32 vcc, s14, v1
	s_cmp_eq_u64 vcc, exec
	s_cselect_b64 vcc, -1, 0
	s_add_u32 s2, s20, 0x610000
	s_addc_u32 s3, s21, 0
	s_add_u32 s22, s20, 0xa10000
	s_addc_u32 s23, s21, 0
	v_max_f32_e32 v68, 0xf149f2ca, v0
	v_lshl_add_u64 v[0:1], s[22:23], 0, v[132:133]
	v_lshl_add_u64 v[2:3], s[22:23], 0, v[134:135]
	v_lshl_add_u64 v[0:1], v[0:1], 0, v[188:189]
	v_lshl_add_u64 v[2:3], v[2:3], 0, v[188:189]
	global_load_dwordx4 v[48:51], v[0:1], off
	global_load_dwordx4 v[52:55], v[2:3], off
	v_lshl_add_u64 v[0:1], s[2:3], 0, v[132:133]
	v_lshl_add_u64 v[2:3], s[2:3], 0, v[134:135]
	s_add_u32 s2, s20, 0x620000
	v_lshl_add_u64 v[0:1], v[0:1], 0, v[188:189]
	s_addc_u32 s3, s21, 0
	v_lshl_add_u64 v[2:3], v[2:3], 0, v[188:189]
	global_load_dwordx4 v[56:59], v[0:1], off
	global_load_dwordx4 v[60:63], v[2:3], off
	s_add_u32 s20, s20, 0xa20000
	v_lshl_add_u64 v[0:1], s[2:3], 0, v[134:135]
	s_addc_u32 s21, s21, 0
	v_lshl_add_u64 v[0:1], v[0:1], 0, v[188:189]
	v_lshl_add_u64 v[2:3], s[2:3], 0, v[132:133]
	v_lshl_add_u64 v[2:3], v[2:3], 0, v[188:189]
	global_load_dwordx4 v[140:143], v[0:1], off
	global_load_dwordx4 v[136:139], v[2:3], off
	v_lshl_add_u64 v[0:1], s[20:21], 0, v[134:135]
	v_lshl_add_u64 v[0:1], v[0:1], 0, v[188:189]
	v_lshl_add_u64 v[2:3], s[20:21], 0, v[132:133]
	v_lshl_add_u64 v[2:3], v[2:3], 0, v[188:189]
	global_load_dwordx4 v[132:135], v[0:1], off
	global_load_dwordx4 v[128:131], v[2:3], off
	v_sub_f32_e32 v0, 0xf149f2ca, v68
	v_mul_f32_e32 v0, 0x3e0293ee, v0
	v_exp_f32_e32 v70, v0
	v_cndmask_b32_e32 v168, v68, v246, vcc
	v_mul_f32_e32 v68, 0xbe0293ee, v168
	v_fmamk_f32 v32, v32, 0x3e0293ee, v68
	v_cndmask_b32_e64 v212, v70, 1.0, vcc
	v_mov_b32_e32 v70, v68
	v_fmamk_f32 v33, v33, 0x3e0293ee, v68
	v_fmamk_f32 v34, v34, 0x3e0293ee, v68
	v_fmamk_f32 v35, v35, 0x3e0293ee, v68
	v_fmamk_f32 v36, v36, 0x3e0293ee, v68
	v_fmamk_f32 v37, v37, 0x3e0293ee, v68
	v_fmamk_f32 v38, v38, 0x3e0293ee, v68
	v_fmamk_f32 v39, v39, 0x3e0293ee, v68
	v_fmamk_f32 v40, v40, 0x3e0293ee, v68
	v_fmamk_f32 v41, v41, 0x3e0293ee, v68
	v_fmamk_f32 v42, v42, 0x3e0293ee, v68
	v_fmamk_f32 v43, v43, 0x3e0293ee, v68
	v_fmamk_f32 v44, v44, 0x3e0293ee, v68
	v_fmamk_f32 v45, v45, 0x3e0293ee, v68
	v_fmamk_f32 v46, v46, 0x3e0293ee, v68
	v_fmac_f32_e32 v70, 0x3e0293ee, v47
	s_mov_b32 s20, s17
	s_mov_b32 s21, s17
	s_mov_b32 s22, s17
	s_mov_b32 s23, s17
	v_mov_b64_e32 v[0:1], s[16:17]
	v_exp_f32_e32 v216, v32
	v_exp_f32_e32 v230, v33
	v_exp_f32_e32 v174, v34
	v_exp_f32_e32 v219, v35
	v_exp_f32_e32 v173, v36
	v_exp_f32_e32 v175, v37
	v_exp_f32_e32 v163, v38
	v_exp_f32_e32 v172, v39
	v_exp_f32_e32 v164, v40
	v_exp_f32_e32 v171, v41
	v_exp_f32_e32 v165, v42
	v_exp_f32_e32 v170, v43
	v_exp_f32_e32 v166, v44
	v_exp_f32_e32 v169, v45
	v_exp_f32_e32 v145, v46
	v_exp_f32_e32 v167, v70
	v_mov_b64_e32 v[14:15], s[30:31]
	s_waitcnt vmcnt(4)
	v_mov_b64_e32 v[2:3], s[18:19]
	v_mov_b64_e32 v[4:5], s[20:21]
	v_mov_b64_e32 v[6:7], s[22:23]
	v_mov_b64_e32 v[8:9], s[24:25]
	v_mov_b64_e32 v[10:11], s[26:27]
	v_mov_b64_e32 v[12:13], s[28:29]
	v_pk_fma_f32 v[152:153], v[30:31], s[88:89], v[68:69] op_sel_hi:[1,0,0]
	v_pk_fma_f32 v[154:155], v[28:29], s[88:89], v[68:69] op_sel_hi:[1,0,0]
	v_pk_fma_f32 v[160:161], v[26:27], s[88:89], v[68:69] op_sel_hi:[1,0,0]
	v_pk_fma_f32 v[146:147], v[24:25], s[88:89], v[68:69] op_sel_hi:[1,0,0]
	v_pk_fma_f32 v[148:149], v[22:23], s[88:89], v[68:69] op_sel_hi:[1,0,0]
	v_pk_fma_f32 v[150:151], v[20:21], s[88:89], v[68:69] op_sel_hi:[1,0,0]
	v_pk_fma_f32 v[156:157], v[18:19], s[88:89], v[68:69] op_sel_hi:[1,0,0]
	v_pk_fma_f32 v[158:159], v[16:17], s[88:89], v[68:69] op_sel_hi:[1,0,0]
	s_waitcnt vmcnt(7)
	ds_write_b128 v200, v[48:51] offset:16384
	s_waitcnt vmcnt(6)
	ds_write_b128 v201, v[52:55] offset:16384
	s_waitcnt vmcnt(5)
	ds_write_b128 v202, v[56:59] offset:49152
	s_waitcnt vmcnt(4)
	ds_write_b128 v203, v[60:63] offset:49152
	s_addk_i32 s4, 0x4000
	v_mov_b64_e32 v[62:63], v[14:15]
	v_mov_b64_e32 v[46:47], v[14:15]
	v_mov_b64_e32 v[30:31], v[14:15]
	v_cmp_gt_u32_e64 s[2:3], 32, v196
	v_lshl_add_u32 v189, v227, 2, v191
	v_add_u32_e32 v198, s4, v69
	v_mov_b64_e32 v[60:61], v[12:13]
	v_mov_b64_e32 v[58:59], v[10:11]
	v_mov_b64_e32 v[56:57], v[8:9]
	v_mov_b64_e32 v[54:55], v[6:7]
	v_mov_b64_e32 v[52:53], v[4:5]
	v_mov_b64_e32 v[50:51], v[2:3]
	v_mov_b64_e32 v[48:49], v[0:1]
	v_mov_b64_e32 v[44:45], v[12:13]
	v_mov_b64_e32 v[42:43], v[10:11]
	v_mov_b64_e32 v[40:41], v[8:9]
	v_mov_b64_e32 v[38:39], v[6:7]
	v_mov_b64_e32 v[36:37], v[4:5]
	v_mov_b64_e32 v[34:35], v[2:3]
	v_mov_b64_e32 v[32:33], v[0:1]
	v_mov_b64_e32 v[28:29], v[12:13]
	v_mov_b64_e32 v[26:27], v[10:11]
	v_mov_b64_e32 v[24:25], v[8:9]
	v_mov_b64_e32 v[22:23], v[6:7]
	v_mov_b64_e32 v[20:21], v[4:5]
	v_mov_b64_e32 v[18:19], v[2:3]
	v_mov_b64_e32 v[16:17], v[0:1]
	s_waitcnt lgkmcnt(0)
	s_barrier
	v_add_u32_e32 v222, v192, v176
	v_add_u32_e32 v243, v194, v176
.LBB0_709:
	s_add_i32 s20, s85, -3
	ds_read_b128 v[64:67], v204 offset:49152
	ds_read_b128 v[68:71], v204 offset:57344
	ds_read_b128 v[178:181], v207 offset:49152
	ds_read_b128 v[182:185], v207 offset:57344
	v_exp_f32_e32 v144, v158
	v_exp_f32_e32 v158, v159
	s_waitcnt lgkmcnt(3)
	v_mfma_f32_32x32x16_bf16 v[80:95], v[64:67], v[124:127], 0
	v_exp_f32_e32 v159, v160
	v_add_f32_e32 v160, 0, v216
	v_add_f32_e32 v160, v230, v160
	v_add_f32_e32 v160, v174, v160
	v_add_f32_e32 v160, v219, v160
	v_add_f32_e32 v160, v173, v160
	v_add_f32_e32 v160, v175, v160
	s_waitcnt lgkmcnt(2)
	v_mfma_f32_32x32x16_bf16 v[64:79], v[68:71], v[124:127], 0
	v_add_f32_e32 v160, v163, v160
	v_add_f32_e32 v160, v172, v160
	v_add_f32_e32 v160, v164, v160
	v_add_f32_e32 v160, v171, v160
	v_add_f32_e32 v160, v165, v160
	v_add_f32_e32 v160, v170, v160
	v_add_f32_e32 v160, v166, v160
	s_waitcnt lgkmcnt(1)
	v_mfma_f32_32x32x16_bf16 v[80:95], v[178:181], v[120:123], v[80:95]
	v_add_f32_e32 v160, v169, v160
	v_exp_f32_e32 v156, v156
	v_add_f32_e32 v160, v145, v160
	v_exp_f32_e32 v157, v157
	v_add_f32_e32 v160, v167, v160
	v_exp_f32_e32 v150, v150
	v_add_f32_e32 v160, v144, v160
	s_waitcnt lgkmcnt(0)
	v_mfma_f32_32x32x16_bf16 v[64:79], v[182:185], v[120:123], v[64:79]
	ds_read_b128 v[178:181], v209 offset:49152
	ds_read_b128 v[182:185], v209 offset:57344
	v_exp_f32_e32 v151, v151
	v_add_f32_e32 v160, v158, v160
	v_exp_f32_e32 v148, v148
	v_add_f32_e32 v160, v156, v160
	v_exp_f32_e32 v149, v149
	v_add_f32_e32 v160, v157, v160
	s_waitcnt lgkmcnt(1)
	v_mfma_f32_32x32x16_bf16 v[80:95], v[178:181], v[116:119], v[80:95]
	v_exp_f32_e32 v146, v146
	v_add_f32_e32 v160, v150, v160
	v_exp_f32_e32 v147, v147
	v_add_f32_e32 v160, v151, v160
	v_add_f32_e32 v160, v148, v160
	v_add_f32_e32 v160, v149, v160
	v_exp_f32_e32 v154, v154
	s_waitcnt lgkmcnt(0)
	v_mfma_f32_32x32x16_bf16 v[64:79], v[182:185], v[116:119], v[64:79]
	ds_read_b128 v[178:181], v205 offset:49152
	ds_read_b128 v[182:185], v205 offset:57344
	v_add_f32_e32 v160, v146, v160
	v_exp_f32_e32 v155, v155
	v_add_f32_e32 v160, v147, v160
	v_exp_f32_e32 v152, v152
	v_add_f32_e32 v160, v159, v160
	v_exp_f32_e32 v153, v153
	s_waitcnt lgkmcnt(1)
	v_mfma_f32_32x32x16_bf16 v[80:95], v[178:181], v[112:115], v[80:95]
	s_waitcnt lgkmcnt(0)
	v_mfma_f32_32x32x16_bf16 v[64:79], v[182:185], v[112:115], v[64:79]
	ds_read_b128 v[178:181], v206 offset:49152
	ds_read_b128 v[182:185], v206 offset:57344
	s_waitcnt lgkmcnt(1)
	v_mfma_f32_32x32x16_bf16 v[80:95], v[178:181], v[108:111], v[80:95]
	s_waitcnt lgkmcnt(0)
	v_mfma_f32_32x32x16_bf16 v[64:79], v[182:185], v[108:111], v[64:79]
	ds_read_b128 v[178:181], v208 offset:49152
	ds_read_b128 v[182:185], v208 offset:57344
	s_waitcnt lgkmcnt(1)
	v_mfma_f32_32x32x16_bf16 v[80:95], v[178:181], v[104:107], v[80:95]
	s_waitcnt lgkmcnt(0)
	v_mfma_f32_32x32x16_bf16 v[64:79], v[182:185], v[104:107], v[64:79]
	ds_read_b128 v[178:181], v210 offset:49152
	ds_read_b128 v[182:185], v210 offset:57344
	s_waitcnt lgkmcnt(1)
	v_mfma_f32_32x32x16_bf16 v[80:95], v[178:181], v[100:103], v[80:95]
	s_waitcnt lgkmcnt(0)
	v_mfma_f32_32x32x16_bf16 v[64:79], v[182:185], v[100:103], v[64:79]
	ds_read_b128 v[178:181], v211 offset:49152
	ds_read_b128 v[182:185], v211 offset:57344
	s_waitcnt lgkmcnt(1)
	v_mfma_f32_32x32x16_bf16 v[80:95], v[178:181], v[96:99], v[80:95]
	v_exp_f32_e32 v179, v161
	s_nop 0
	v_add_f32_e32 v160, v179, v160
	v_add_f32_e32 v160, v154, v160
	v_add_f32_e32 v160, v155, v160
	s_waitcnt lgkmcnt(0)
	v_mfma_f32_32x32x16_bf16 v[64:79], v[182:185], v[96:99], v[64:79]
	v_add_f32_e32 v160, v152, v160
	v_add_f32_e32 v213, v153, v160
	v_mov_b32_e32 v214, v213
	v_cvt_pk_bf16_f32 v160, v216, v230
	v_cvt_pk_bf16_f32 v161, v174, v219
	v_cvt_pk_bf16_f32 v162, v173, v175
	s_nop 1
	v_permlane32_swap_b32_e32 v213, v214
	v_cvt_pk_bf16_f32 v163, v163, v172
	v_permlane32_swap_b32_e32 v160, v162
	v_cvt_pk_bf16_f32 v164, v164, v171
	v_cvt_pk_bf16_f32 v165, v165, v170
	v_cvt_pk_bf16_f32 v166, v166, v169
	v_cvt_pk_bf16_f32 v167, v145, v167
	v_cvt_pk_bf16_f32 v170, v144, v158
	v_cvt_pk_bf16_f32 v171, v156, v157
	v_cvt_pk_bf16_f32 v172, v150, v151
	v_cvt_pk_bf16_f32 v173, v148, v149
	v_cvt_pk_bf16_f32 v178, v146, v147
	v_cvt_pk_bf16_f32 v179, v159, v179
	v_cvt_pk_bf16_f32 v180, v154, v155
	v_cvt_pk_bf16_f32 v181, v152, v153
	v_permlane32_swap_b32_e32 v161, v163
	v_permlane32_swap_b32_e32 v164, v166
	v_permlane32_swap_b32_e32 v165, v167
	v_permlane32_swap_b32_e32 v170, v172
	v_permlane32_swap_b32_e32 v171, v173
	v_permlane32_swap_b32_e32 v178, v180
	v_permlane32_swap_b32_e32 v179, v181
	s_cmp_lt_u32 s20, 6
	s_cselect_b64 s[4:5], -1, 0
	s_and_b64 s[18:19], s[4:5], exec
	s_cselect_b32 s16, 0, -8
	s_add_i32 s16, s16, s85
	s_add_i32 s16, s16, -1
	s_and_b64 s[4:5], s[4:5], exec
	s_cselect_b32 s19, s49, s43
	s_cselect_b32 s18, s48, s36
	s_cselect_b32 s21, s57, s52
	s_cselect_b32 s22, s56, s44
	s_lshl_b64 s[4:5], s[16:17], 16
	s_add_u32 s18, s18, s4
	s_addc_u32 s19, s19, s5
	s_add_u32 s4, s22, s4
	s_addc_u32 s5, s21, s5
	global_load_dwordx4 v[144:147], v222, s[4:5]
	global_load_dwordx4 v[148:151], v243, s[4:5]
	global_load_dwordx4 v[152:155], v222, s[18:19]
	global_load_dwordx4 v[156:159], v243, s[18:19]
	ds_read_b64_tr_b16 v[182:183], v199 offset:0
	ds_read_b64_tr_b16 v[184:185], v199 offset:0x800
	ds_read_b64_tr_b16 v[216:217], v199 offset:0x1000
	ds_read_b64_tr_b16 v[218:219], v199 offset:0x1800
	ds_read_b64_tr_b16 v[230:231], v199 offset:0x2000
	ds_read_b64_tr_b16 v[232:233], v199 offset:0x2800
	ds_read_b64_tr_b16 v[234:235], v199 offset:0x3000
	ds_read_b64_tr_b16 v[236:237], v199 offset:0x3800
	s_waitcnt lgkmcnt(0)
	s_nop 0
	v_mfma_f32_32x32x16_bf16 v[0:15], v[160:163], v[182:185], v[0:15]
	ds_read_b64_tr_b16 v[182:183], v199 offset:0x200
	ds_read_b64_tr_b16 v[184:185], v199 offset:0xa00
	v_mfma_f32_32x32x16_bf16 v[0:15], v[164:167], v[216:219], v[0:15]
	ds_read_b64_tr_b16 v[216:217], v199 offset:0x1200
	ds_read_b64_tr_b16 v[218:219], v199 offset:0x1a00
	v_mfma_f32_32x32x16_bf16 v[0:15], v[170:173], v[230:233], v[0:15]
	ds_read_b64_tr_b16 v[230:231], v199 offset:0x2200
	ds_read_b64_tr_b16 v[232:233], v199 offset:0x2a00
	v_mfma_f32_32x32x16_bf16 v[0:15], v[178:181], v[234:237], v[0:15]
	ds_read_b64_tr_b16 v[234:235], v199 offset:0x3200
	ds_read_b64_tr_b16 v[236:237], v199 offset:0x3a00
	s_waitcnt lgkmcnt(0)
	v_mfma_f32_32x32x16_bf16 v[48:63], v[160:163], v[182:185], v[48:63]
	ds_read_b64_tr_b16 v[182:183], v199 offset:0x400
	ds_read_b64_tr_b16 v[184:185], v199 offset:0xc00
	v_mfma_f32_32x32x16_bf16 v[48:63], v[164:167], v[216:219], v[48:63]
	ds_read_b64_tr_b16 v[216:217], v199 offset:0x1400
	ds_read_b64_tr_b16 v[218:219], v199 offset:0x1c00
	v_mfma_f32_32x32x16_bf16 v[48:63], v[170:173], v[230:233], v[48:63]
	ds_read_b64_tr_b16 v[230:231], v199 offset:0x2400
	ds_read_b64_tr_b16 v[232:233], v199 offset:0x2c00
	v_mfma_f32_32x32x16_bf16 v[48:63], v[178:181], v[234:237], v[48:63]
	ds_read_b64_tr_b16 v[234:235], v199 offset:0x3400
	ds_read_b64_tr_b16 v[236:237], v199 offset:0x3c00
	s_waitcnt lgkmcnt(0)
	v_mfma_f32_32x32x16_bf16 v[32:47], v[160:163], v[182:185], v[32:47]
	ds_read_b64_tr_b16 v[182:183], v199 offset:0x600
	ds_read_b64_tr_b16 v[184:185], v199 offset:0xe00
	v_mfma_f32_32x32x16_bf16 v[32:47], v[164:167], v[216:219], v[32:47]
	ds_read_b64_tr_b16 v[216:217], v199 offset:0x1600
	ds_read_b64_tr_b16 v[218:219], v199 offset:0x1e00
	v_mfma_f32_32x32x16_bf16 v[32:47], v[170:173], v[230:233], v[32:47]
	ds_read_b64_tr_b16 v[230:231], v199 offset:0x2600
	ds_read_b64_tr_b16 v[232:233], v199 offset:0x2e00
	v_mfma_f32_32x32x16_bf16 v[32:47], v[178:181], v[234:237], v[32:47]
	ds_read_b64_tr_b16 v[234:235], v199 offset:0x3600
	ds_read_b64_tr_b16 v[236:237], v199 offset:0x3e00
	s_waitcnt lgkmcnt(0)
	v_mfma_f32_32x32x16_bf16 v[16:31], v[160:163], v[182:185], v[16:31]
	v_max_f32_e32 v160, v81, v81
	v_max_f32_e32 v161, v80, v80
	v_max_f32_e32 v160, v161, v160
	v_max3_f32 v160, v160, v82, v83
	v_max3_f32 v160, v160, v84, v85
	v_max3_f32 v160, v160, v86, v87
	v_max3_f32 v160, v160, v88, v89
	v_max3_f32 v160, v160, v90, v91
	v_max3_f32 v160, v160, v92, v93
	v_mfma_f32_32x32x16_bf16 v[16:31], v[164:167], v[216:219], v[16:31]
	v_max3_f32 v160, v160, v94, v95
	v_max3_f32 v160, v160, v64, v65
	v_max3_f32 v160, v160, v66, v67
	v_max3_f32 v160, v160, v68, v69
	v_max3_f32 v160, v160, v70, v71
	v_max3_f32 v160, v160, v72, v73
	v_max3_f32 v160, v160, v74, v75
	v_max3_f32 v160, v160, v76, v77
	v_mfma_f32_32x32x16_bf16 v[16:31], v[170:173], v[230:233], v[16:31]
	v_max3_f32 v160, v160, v78, v79
	v_mov_b32_e32 v161, v160
	s_nop 1
	v_permlane32_swap_b32_e32 v160, v161
	v_max_f32_e32 v161, v161, v161
	v_max_f32_e32 v160, v160, v160
	v_max_f32_e32 v160, v160, v161
	v_sub_f32_e32 v161, v160, v168
	v_cmp_ge_f32_e32 vcc, s14, v161
	v_max_f32_e32 v161, v168, v168
	v_max_f32_e32 v160, v161, v160
	v_mfma_f32_32x32x16_bf16 v[16:31], v[178:181], v[234:237], v[16:31]
	v_sub_f32_e32 v161, v168, v160
	v_mul_f32_e32 v161, 0x3e0293ee, v161
	v_exp_f32_e32 v161, v161
	s_cmp_eq_u64 vcc, exec
	s_cselect_b64 s[4:5], -1, 0
	s_barrier
	s_waitcnt vmcnt(4)
	v_cndmask_b32_e64 v215, v161, 1.0, s[4:5]
	v_cmp_gt_f32_e32 vcc, 1.0, v215
	s_waitcnt vmcnt(4)
	ds_write_b128 v200, v[128:131]
	ds_write_b128 v201, v[132:135]
	ds_write_b128 v202, v[136:139] offset:32768
	ds_write_b128 v203, v[140:143] offset:32768
	s_cbranch_vccz .LBB0_713
	s_and_saveexec_b64 s[18:19], s[2:3]
	ds_write_b32 v189, v215 offset:128
	s_or_b64 exec, exec, s[18:19]
	s_waitcnt lgkmcnt(0)
	v_add_u32_e32 v161, v191, v190
	ds_read_b128 v[162:165], v161 offset:224
	ds_read_b128 v[170:173], v161 offset:192
	ds_read_b128 v[178:181], v161 offset:160
	ds_read_b128 v[182:185], v161 offset:128
	s_waitcnt lgkmcnt(3)
	v_pk_mul_f32 v[12:13], v[12:13], v[162:163]
	s_waitcnt lgkmcnt(2)
	v_pk_mul_f32 v[8:9], v[8:9], v[170:171]
	s_waitcnt lgkmcnt(1)
	v_pk_mul_f32 v[4:5], v[4:5], v[178:179]
	v_pk_mul_f32 v[14:15], v[14:15], v[164:165]
	v_pk_mul_f32 v[10:11], v[10:11], v[172:173]
	v_pk_mul_f32 v[6:7], v[6:7], v[180:181]
	s_waitcnt lgkmcnt(0)
	v_pk_mul_f32 v[2:3], v[2:3], v[184:185]
	v_pk_mul_f32 v[0:1], v[0:1], v[182:183]
	v_pk_mul_f32 v[60:61], v[60:61], v[162:163]
	v_pk_mul_f32 v[56:57], v[56:57], v[170:171]
	v_pk_mul_f32 v[52:53], v[52:53], v[178:179]
	v_pk_mul_f32 v[62:63], v[62:63], v[164:165]
	v_pk_mul_f32 v[58:59], v[58:59], v[172:173]
	v_pk_mul_f32 v[54:55], v[54:55], v[180:181]
	v_pk_mul_f32 v[50:51], v[50:51], v[184:185]
	v_pk_mul_f32 v[48:49], v[48:49], v[182:183]
	v_pk_mul_f32 v[44:45], v[44:45], v[162:163]
	v_pk_mul_f32 v[40:41], v[40:41], v[170:171]
	v_pk_mul_f32 v[36:37], v[36:37], v[178:179]
	v_pk_mul_f32 v[46:47], v[46:47], v[164:165]
	v_pk_mul_f32 v[42:43], v[42:43], v[172:173]
	v_pk_mul_f32 v[38:39], v[38:39], v[180:181]
	v_pk_mul_f32 v[34:35], v[34:35], v[184:185]
	v_pk_mul_f32 v[32:33], v[32:33], v[182:183]
	v_pk_mul_f32 v[28:29], v[28:29], v[162:163]
	v_pk_mul_f32 v[24:25], v[24:25], v[170:171]
	v_pk_mul_f32 v[20:21], v[20:21], v[178:179]
	v_pk_mul_f32 v[30:31], v[30:31], v[164:165]
	v_pk_mul_f32 v[26:27], v[26:27], v[172:173]
	v_pk_mul_f32 v[22:23], v[22:23], v[180:181]
	v_pk_mul_f32 v[18:19], v[18:19], v[184:185]
	v_pk_mul_f32 v[16:17], v[16:17], v[182:183]
.LBB0_713:
	v_cndmask_b32_e64 v216, v160, v168, s[4:5]
	v_mul_f32_e32 v217, 0xbe0293ee, v216
	v_fmamk_f32 v80, v80, 0x3e0293ee, v217
	v_fmamk_f32 v81, v81, 0x3e0293ee, v217
	v_fmamk_f32 v82, v82, 0x3e0293ee, v217
	v_fmamk_f32 v83, v83, 0x3e0293ee, v217
	v_fmamk_f32 v84, v84, 0x3e0293ee, v217
	v_fmamk_f32 v85, v85, 0x3e0293ee, v217
	v_fmamk_f32 v86, v86, 0x3e0293ee, v217
	v_fmamk_f32 v87, v87, 0x3e0293ee, v217
	v_fmamk_f32 v88, v88, 0x3e0293ee, v217
	v_fmamk_f32 v89, v89, 0x3e0293ee, v217
	v_fmamk_f32 v90, v90, 0x3e0293ee, v217
	v_fmamk_f32 v91, v91, 0x3e0293ee, v217
	v_fmamk_f32 v92, v92, 0x3e0293ee, v217
	v_fmamk_f32 v93, v93, 0x3e0293ee, v217
	v_fmamk_f32 v94, v94, 0x3e0293ee, v217
	v_fmamk_f32 v95, v95, 0x3e0293ee, v217
	v_exp_f32_e32 v160, v80
	v_exp_f32_e32 v175, v81
	v_exp_f32_e32 v161, v82
	v_exp_f32_e32 v174, v83
	v_exp_f32_e32 v162, v84
	v_exp_f32_e32 v173, v85
	v_exp_f32_e32 v163, v86
	v_exp_f32_e32 v172, v87
	v_exp_f32_e32 v164, v88
	v_exp_f32_e32 v171, v89
	v_exp_f32_e32 v165, v90
	v_exp_f32_e32 v170, v91
	v_exp_f32_e32 v166, v92
	v_exp_f32_e32 v169, v93
	v_exp_f32_e32 v167, v94
	v_exp_f32_e32 v168, v95
	v_fmamk_f32 v236, v64, 0x3e0293ee, v217
	v_fmamk_f32 v237, v65, 0x3e0293ee, v217
	v_fmamk_f32 v238, v66, 0x3e0293ee, v217
	v_fmamk_f32 v239, v67, 0x3e0293ee, v217
	v_fmamk_f32 v240, v68, 0x3e0293ee, v217
	v_fmamk_f32 v219, v69, 0x3e0293ee, v217
	v_fmamk_f32 v230, v70, 0x3e0293ee, v217
	v_fmamk_f32 v231, v71, 0x3e0293ee, v217
	v_fmamk_f32 v232, v72, 0x3e0293ee, v217
	v_fmamk_f32 v233, v73, 0x3e0293ee, v217
	v_fmamk_f32 v234, v74, 0x3e0293ee, v217
	v_fmamk_f32 v235, v75, 0x3e0293ee, v217
	v_fmamk_f32 v218, v76, 0x3e0293ee, v217
	v_fmamk_f32 v241, v77, 0x3e0293ee, v217
	v_fmamk_f32 v242, v78, 0x3e0293ee, v217
	v_fmac_f32_e32 v217, 0x3e0293ee, v79
	s_waitcnt lgkmcnt(0)
	s_barrier
	ds_read_b128 v[64:67], v204 offset:32768
	ds_read_b128 v[68:71], v204 offset:40960
	ds_read_b128 v[178:181], v207 offset:32768
	ds_read_b128 v[182:185], v207 offset:40960
	v_exp_f32_e32 v186, v232
	v_exp_f32_e32 v232, v217
	s_waitcnt lgkmcnt(3)
	v_mfma_f32_32x32x16_bf16 v[80:95], v[64:67], v[124:127], 0
	v_add_f32_e32 v217, 0, v160
	v_add_f32_e32 v217, v175, v217
	v_add_f32_e32 v217, v161, v217
	v_add_f32_e32 v217, v174, v217
	v_add_f32_e32 v217, v162, v217
	v_add_f32_e32 v217, v173, v217
	v_add_f32_e32 v217, v163, v217
	s_waitcnt lgkmcnt(2)
	v_mfma_f32_32x32x16_bf16 v[64:79], v[68:71], v[124:127], 0
	v_add_f32_e32 v217, v172, v217
	v_add_f32_e32 v217, v164, v217
	v_add_f32_e32 v217, v171, v217
	v_add_f32_e32 v217, v165, v217
	v_add_f32_e32 v217, v170, v217
	v_add_f32_e32 v217, v166, v217
	v_add_f32_e32 v217, v169, v217
	s_waitcnt lgkmcnt(1)
	v_mfma_f32_32x32x16_bf16 v[80:95], v[178:181], v[120:123], v[80:95]
	v_add_f32_e32 v217, v167, v217
	v_add_f32_e32 v217, v168, v217
	v_exp_f32_e32 v187, v233
	v_exp_f32_e32 v224, v235
	v_exp_f32_e32 v225, v218
	s_waitcnt lgkmcnt(0)
	v_mfma_f32_32x32x16_bf16 v[64:79], v[182:185], v[120:123], v[64:79]
	ds_read_b128 v[178:181], v209 offset:32768
	ds_read_b128 v[182:185], v209 offset:40960
	s_waitcnt lgkmcnt(1)
	v_mfma_f32_32x32x16_bf16 v[80:95], v[178:181], v[116:119], v[80:95]
	s_waitcnt lgkmcnt(0)
	v_mfma_f32_32x32x16_bf16 v[64:79], v[182:185], v[116:119], v[64:79]
	ds_read_b128 v[178:181], v205 offset:32768
	ds_read_b128 v[182:185], v205 offset:40960
	s_waitcnt lgkmcnt(1)
	v_mfma_f32_32x32x16_bf16 v[80:95], v[178:181], v[112:115], v[80:95]
	s_waitcnt lgkmcnt(0)
	v_mfma_f32_32x32x16_bf16 v[64:79], v[182:185], v[112:115], v[64:79]
	ds_read_b128 v[178:181], v206 offset:32768
	ds_read_b128 v[182:185], v206 offset:40960
	s_waitcnt lgkmcnt(1)
	v_mfma_f32_32x32x16_bf16 v[80:95], v[178:181], v[108:111], v[80:95]
	s_waitcnt lgkmcnt(0)
	v_mfma_f32_32x32x16_bf16 v[64:79], v[182:185], v[108:111], v[64:79]
	ds_read_b128 v[178:181], v208 offset:32768
	ds_read_b128 v[182:185], v208 offset:40960
	s_waitcnt lgkmcnt(1)
	v_mfma_f32_32x32x16_bf16 v[80:95], v[178:181], v[104:107], v[80:95]
	s_waitcnt lgkmcnt(0)
	v_mfma_f32_32x32x16_bf16 v[64:79], v[182:185], v[104:107], v[64:79]
	ds_read_b128 v[178:181], v210 offset:32768
	ds_read_b128 v[182:185], v210 offset:40960
	s_waitcnt lgkmcnt(1)
	v_mfma_f32_32x32x16_bf16 v[80:95], v[178:181], v[100:103], v[80:95]
	s_waitcnt lgkmcnt(0)
	v_mfma_f32_32x32x16_bf16 v[64:79], v[182:185], v[100:103], v[64:79]
	ds_read_b128 v[178:181], v211 offset:32768
	ds_read_b128 v[182:185], v211 offset:40960
	v_cvt_pk_bf16_f32 v160, v160, v175
	v_cvt_pk_bf16_f32 v161, v161, v174
	v_cvt_pk_bf16_f32 v162, v162, v173
	v_cvt_pk_bf16_f32 v163, v163, v172
	v_cvt_pk_bf16_f32 v164, v164, v171
	v_cvt_pk_bf16_f32 v165, v165, v170
	s_waitcnt lgkmcnt(1)
	v_mfma_f32_32x32x16_bf16 v[80:95], v[178:181], v[96:99], v[80:95]
	v_exp_f32_e32 v178, v236
	v_exp_f32_e32 v179, v237
	v_exp_f32_e32 v180, v238
	v_exp_f32_e32 v181, v239
	v_add_f32_e32 v217, v178, v217
	v_add_f32_e32 v217, v179, v217
	v_add_f32_e32 v217, v180, v217
	s_waitcnt lgkmcnt(0)
	v_mfma_f32_32x32x16_bf16 v[64:79], v[182:185], v[96:99], v[64:79]
	v_exp_f32_e32 v182, v240
	v_exp_f32_e32 v183, v219
	v_exp_f32_e32 v184, v230
	v_exp_f32_e32 v185, v231
	v_add_f32_e32 v217, v181, v217
	v_add_f32_e32 v217, v182, v217
	v_add_f32_e32 v217, v183, v217
	v_exp_f32_e32 v219, v234
	v_add_f32_e32 v217, v184, v217
	v_add_f32_e32 v217, v185, v217
	v_add_f32_e32 v217, v186, v217
	v_exp_f32_e32 v230, v241
	v_add_f32_e32 v217, v187, v217
	v_exp_f32_e32 v231, v242
	v_add_f32_e32 v217, v219, v217
	v_add_f32_e32 v217, v224, v217
	v_add_f32_e32 v217, v225, v217
	v_add_f32_e32 v217, v230, v217
	v_add_f32_e32 v217, v231, v217
	v_add_f32_e32 v217, v232, v217
	v_mov_b32_e32 v218, v217
	v_cvt_pk_bf16_f32 v166, v166, v169
	v_cvt_pk_bf16_f32 v167, v167, v168
	v_cvt_pk_bf16_f32 v168, v178, v179
	v_cvt_pk_bf16_f32 v169, v180, v181
	v_cvt_pk_bf16_f32 v170, v182, v183
	v_cvt_pk_bf16_f32 v171, v184, v185
	v_cvt_pk_bf16_f32 v172, v186, v187
	v_cvt_pk_bf16_f32 v173, v219, v224
	v_cvt_pk_bf16_f32 v174, v225, v230
	v_cvt_pk_bf16_f32 v175, v231, v232
	s_nop 1
	v_permlane32_swap_b32_e32 v217, v218
	v_permlane32_swap_b32_e32 v160, v162
	v_permlane32_swap_b32_e32 v161, v163
	v_permlane32_swap_b32_e32 v164, v166
	v_permlane32_swap_b32_e32 v165, v167
	v_permlane32_swap_b32_e32 v168, v170
	v_permlane32_swap_b32_e32 v169, v171
	v_permlane32_swap_b32_e32 v172, v174
	v_permlane32_swap_b32_e32 v173, v175
	s_cmpk_gt_u32 s20, 0x44
	s_cbranch_scc1 .LBB0_715
	s_cmp_lt_u32 s20, 5
	s_cselect_b64 s[4:5], -1, 0
	s_and_b64 s[18:19], s[4:5], exec
	s_cselect_b32 s16, 0, -8
	s_add_i32 s16, s16, s85
	s_and_b64 s[4:5], s[4:5], exec
	s_cselect_b32 s19, s49, s43
	s_cselect_b32 s18, s48, s36
	s_cselect_b32 s21, s57, s52
	s_cselect_b32 s22, s56, s44
	s_lshl_b64 s[4:5], s[16:17], 16
	s_add_u32 s18, s18, s4
	s_addc_u32 s19, s19, s5
	s_add_u32 s4, s22, s4
	s_addc_u32 s5, s21, s5
	global_load_dwordx4 v[128:131], v222, s[4:5]
	global_load_dwordx4 v[132:135], v243, s[4:5]
	global_load_dwordx4 v[136:139], v222, s[18:19]
	global_load_dwordx4 v[140:143], v243, s[18:19]
